# v58 + early invalidate in the cg grid sync; XCD leader no longer waits for its release atomics before the closing barrier
# baseline (speedup 1.0000x reference)
; #define KP (kparams())
; __global__ void __launch_bounds__(512) fwd_kernel(Params p_unused) {
;     ...
;     if (bid == 0) for (int i = threadIdx.x; i < CTL_WORDS; i += 512) barw[i] = 0u;
;     if (threadIdx.x < 4) xst[threadIdx.x] = 0u;
;     phase0(KP, (float*)smem, bid, G);
;     grid.sync();
.LBB0_58:
	s_or_b64 exec, exec, s[4:5]
	v_lshrrev_b32_e32 v1, 20, v0
	v_lshrrev_b32_e32 v0, 10, v0
	v_or_b32_e32 v0, v0, v1
	s_movk_i32 s3, 0x3ff
	v_and_or_b32 v0, v0, s3, v172
	v_cmp_eq_u32_e32 vcc, 0, v0
	s_waitcnt lgkmcnt(0)
	s_barrier
	s_and_saveexec_b64 s[4:5], vcc
	s_cbranch_execz .LBB0_68
	buffer_wbl2 sc1
	buffer_inv sc1
	s_waitcnt vmcnt(0)
	s_load_dwordx2 s[0:1], s[42:43], 0x58
	v_mov_b32_e32 v2, 0
	s_mov_b64 s[6:7], exec
	v_mbcnt_lo_u32_b32 v1, s6, 0
	v_mbcnt_hi_u32_b32 v1, s7, v1
	s_waitcnt lgkmcnt(0)
	global_load_dword v0, v2, s[0:1] offset:40
	v_cmp_eq_u32_e32 vcc, 0, v1
	s_and_saveexec_b64 s[8:9], vcc
	s_cbranch_execz .LBB0_61
	s_bcnt1_i32_b64 s3, s[6:7]
	v_mov_b32_e32 v3, s3
	global_atomic_add v3, v2, v3, s[0:1] offset:32 sc0

; #define LAS __attribute__((address_space(3)))
; __device__ __forceinline__ unsigned xb_add(unsigned* p, unsigned v) { return __hip_atomic_fetch_add(p, v, __ATOMIC_RELAXED, __HIP_MEMORY_SCOPE_AGENT); }
; __device__ __forceinline__ unsigned xb_xcc_id() { return (unsigned)__builtin_amdgcn_s_getreg((3 << 11) | 20) & 0xFu; }
; __device__ __forceinline__ XcdBarrier xcd_barrier_post(unsigned* bar, volatile LAS unsigned* st) {
;     XcdBarrier b; b.bar = bar; b.x = xb_xcc_id(); b.st = st;
;     if (threadIdx.x == 0) (void)xb_add(&bar[XB_XCNT(b.x)], 1u);
;     return b;
; __global__ void __launch_bounds__(512) fwd_kernel(Params p_unused) {
;     ...
;     grid.sync();
;     const XcdBarrier xb = xcd_barrier_post(barw, xst);
.LBB0_66:
	s_sleep 1
	global_load_dword v2, v0, s[0:1] offset:32 sc1
	s_waitcnt vmcnt(0)
	v_and_b32_e32 v2, 0xffff0000, v2
	v_cmp_ne_u32_e32 vcc, v2, v1
	s_or_b64 s[6:7], vcc, s[6:7]
	s_andn2_b64 exec, exec, s[6:7]
	s_cbranch_execnz .LBB0_66
.LBB0_67:
	s_nop 0
.LBB0_68:
	s_or_b64 exec, exec, s[4:5]
	s_barrier
	s_getreg_b32 s0, hwreg(HW_REG_XCC_ID, 0, 4)
	s_and_b32 s0, s0, 15
	v_writelane_b32 v252, s0, 5
	v_cmp_eq_u32_e64 s[4:5], 0, v172
	s_mov_b64 s[0:1], exec
	s_nop 0
	v_writelane_b32 v252, s4, 6
	s_nop 1
	v_writelane_b32 v252, s5, 7
	s_and_b64 s[4:5], s[0:1], s[4:5]
	s_mov_b64 exec, s[4:5]
	s_cbranch_execz .LBB0_71
	s_mov_b64 s[4:5], exec
	v_mbcnt_lo_u32_b32 v0, s4, 0
	v_mbcnt_hi_u32_b32 v0, s5, v0
	v_cmp_eq_u32_e32 vcc, 0, v0
	s_and_b64 s[6:7], exec, vcc
	s_mov_b64 exec, s[6:7]
	s_cbranch_execz .LBB0_71
	v_readlane_b32 s3, v252, 5
	s_lshl_b32 s3, s3, 8
	s_bcnt1_i32_b64 s4, s[4:5]
	v_mov_b32_e32 v0, s3
	v_mov_b32_e32 v1, s4
	global_atomic_add v0, v1, s[84:85] offset:1024

; __device__ __forceinline__ unsigned xb_add(unsigned* p, unsigned v) { return __hip_atomic_fetch_add(p, v, __ATOMIC_RELAXED, __HIP_MEMORY_SCOPE_AGENT); }
; __device__ __forceinline__ void xcd_barrier(const XcdBarrier& b) {
;     ...
;             xb_add(&bar[XB_XGEN(b.x)], 1u);
;             asm volatile("s_waitcnt vmcnt(0)" ::: "memory");
.LBB0_235:
	s_or_b64 exec, exec, s[8:9]
	s_nop 0

; __device__ __forceinline__ unsigned xb_add(unsigned* p, unsigned v) { return __hip_atomic_fetch_add(p, v, __ATOMIC_RELAXED, __HIP_MEMORY_SCOPE_AGENT); }
; __device__ __forceinline__ void xcd_barrier(const XcdBarrier& b) {
;     ...
;             xb_add(&bar[XB_XGEN(b.x)], 1u);
;             asm volatile("s_waitcnt vmcnt(0)" ::: "memory");
.LBB0_464:
	s_or_b64 exec, exec, s[10:11]
	s_nop 0

; __device__ __forceinline__ unsigned xb_add(unsigned* p, unsigned v) { return __hip_atomic_fetch_add(p, v, __ATOMIC_RELAXED, __HIP_MEMORY_SCOPE_AGENT); }
; __device__ __forceinline__ void xcd_barrier(const XcdBarrier& b) {
;     ...
;             xb_add(&bar[XB_XGEN(b.x)], 1u);
;             asm volatile("s_waitcnt vmcnt(0)" ::: "memory");
.LBB0_1138:
	s_or_b64 exec, exec, s[20:21]
	s_nop 0
